# poll-interval tuning: tile-completion gate and GEMM2 row-stat rendezvous poll with s_sleep 1
# baseline (speedup 1.0000x reference)
.Lgate_poll:
	global_load_dword v231, v230, s[6:7] sc1
	s_waitcnt vmcnt(0)
	v_readfirstlane_b32 s4, v231
	s_cmp_ge_u32 s4, s8
	s_cbranch_scc1 .Lgate_ok
	s_sleep 1
	s_add_i32 s9, s9, -1
	s_cmp_eq_u32 s9, 0
	s_cbranch_scc0 .Lgate_poll

.LBB0_582:
	global_load_dword v4, v113, s[4:5] sc1
	s_mov_b64 s[8:9], -1
	s_waitcnt vmcnt(0)
	v_cmp_lt_u32_e32 vcc, 7, v4
	s_cbranch_vccnz .LBB0_581
	s_sleep 1
	global_load_dword v4, v113, s[4:5] sc1
	s_waitcnt vmcnt(0)
	v_cmp_gt_u32_e32 vcc, 8, v4
	s_cbranch_vccz .LBB0_581
	s_sleep 1
	global_load_dword v4, v113, s[4:5] sc1
	s_waitcnt vmcnt(0)
	v_cmp_gt_u32_e32 vcc, 8, v4
	s_cbranch_vccz .LBB0_581
	s_sleep 1
	global_load_dword v4, v113, s[4:5] sc1
	s_waitcnt vmcnt(0)
	v_cmp_gt_u32_e32 vcc, 8, v4
	s_cbranch_vccz .LBB0_581
	s_sleep 1
	global_load_dword v4, v113, s[4:5] sc1
	s_waitcnt vmcnt(0)
	v_cmp_gt_u32_e32 vcc, 8, v4
	s_cbranch_vccz .LBB0_581
	s_add_i32 s10, s10, -5
	s_cmp_eq_u32 s10, 0
	s_cselect_b64 s[8:9], -1, 0
	s_sleep 1
	s_branch .LBB0_581
